# attention unit prologue: forget-cumsum row load issued early with the first load batch (removes a second exposed round trip); first-supertile K/V loads issued after Q and norm-gain loads
# speedup vs baseline: 1.0093x; 1.0037x over previous
.LBB0_140:
	s_or_b64 exec, exec, s[12:13]
	v_readlane_b32 s2, v254, 24
	s_waitcnt vmcnt(0) lgkmcnt(0)
	s_barrier
	v_mov_b32_e32 v0, s2
	ds_read_b32 v0, v0
	s_mov_b64 s[12:13], -1
	s_waitcnt lgkmcnt(0)
	s_barrier
	v_cmp_le_i32_e32 vcc, s86, v0
	v_readfirstlane_b32 s18, v0
	s_cbranch_vccnz .LBB0_137
	s_cmp_gt_i32 s18, 63
	s_cbranch_scc0 .LBB0_170
	s_sub_i32 s3, s18, 64
	s_lshr_b32 s2, s3, 8
	s_bfe_u32 s11, s3, 0x40004
	v_mov_b32_e32 v40, v222
	s_sub_i32 s2, 7, s2
	s_and_b32 s3, s18, 15
	s_lshl_b32 s36, s11, 11
	s_lshl_b32 s4, s11, 17
	v_readlane_b32 s5, v250, 35
	v_ashrrev_i32_e32 v42, 3, v40
	s_add_u32 s14, s5, s4
	v_readlane_b32 s4, v250, 36
	v_ashrrev_i32_e32 v43, 31, v42
	s_addc_u32 s15, s4, 0
	v_lshl_add_u64 v[0:1], s[36:37], 0, v[42:43]
	v_readlane_b32 s4, v250, 37
	v_lshlrev_b64 v[0:1], 11, v[0:1]
	v_readlane_b32 s5, v250, 38
	v_and_b32_e32 v2, 7, v40
	v_readlane_b32 s16, v254, 30
	v_lshl_add_u64 v[0:1], s[4:5], 0, v[0:1]
	s_lshl_b32 s4, s3, 7
	s_mov_b32 s5, s37
	v_lshl_add_u64 v[0:1], v[0:1], 0, s[4:5]
	s_lshl_b32 s4, s3, 22
	v_readlane_b32 s5, v250, 39
	s_add_u32 s4, s5, s4
	v_readlane_b32 s5, v250, 40
	s_addc_u32 s5, s5, 0
	s_lshl_b32 s11, s11, 12
	s_add_u32 s12, s4, s11
	s_addc_u32 s13, s5, 0
	s_lshl_b32 s4, s3, 8
	v_lshlrev_b32_e32 v96, 4, v2
	v_readlane_b32 s17, v254, 31
	s_add_u32 s4, s16, s4
	v_lshl_add_u64 v[174:175], v[0:1], 0, v[96:97]
	s_addc_u32 s5, s17, 0
	v_lshlrev_b32_e32 v0, 5, v2
	global_load_dwordx4 v[98:101], v0, s[4:5] offset:16
	global_load_dwordx4 v[102:105], v0, s[4:5]
	s_lshl_b32 s4, s2, 9
	v_lshlrev_b32_e32 v0, 3, v40
	v_ashrrev_i32_e32 v44, 5, v40
	v_add_u32_e32 v3, 0x200, v40
	s_add_i32 s4, s12, s4
	v_and_b32_e32 v43, 0xf8, v0
	v_ashrrev_i32_e32 v45, 31, v44
	v_ashrrev_i32_e32 v46, 5, v3
	v_lshl_add_u32 v0, v43, 1, s4
	v_lshlrev_b64 v[192:193], 16, v[44:45]
	v_ashrrev_i32_e32 v47, 31, v46
	v_lshl_add_u32 v1, s2, 19, v174
	v_add_u32_e32 v2, v0, v192
	v_lshlrev_b64 v[194:195], 16, v[46:47]
	v_subrev_u32_e32 v1, s74, v1
	v_subrev_u32_e32 v2, s74, v2
	v_add_u32_e32 v3, v0, v194
	v_mov_b32_e32 v106, v1
	v_mov_b32_e32 v110, v2
	v_add_u32_e32 v2, 0x20000, v1
	v_subrev_u32_e32 v3, s74, v3
	v_mov_b32_e32 v114, v2
	v_mov_b32_e32 v118, v3
	v_add_u32_e32 v3, 0x400, v40
	v_ashrrev_i32_e32 v48, 5, v3
	v_ashrrev_i32_e32 v49, 31, v48
	v_lshlrev_b64 v[196:197], 16, v[48:49]
	v_add_u32_e32 v2, 0x40000, v1
	v_add_u32_e32 v3, v0, v196
	v_subrev_u32_e32 v3, s74, v3
	v_mov_b32_e32 v122, v2
	v_mov_b32_e32 v126, v3
	v_add_u32_e32 v2, 0x600, v40
	v_ashrrev_i32_e32 v50, 5, v2
	v_ashrrev_i32_e32 v51, 31, v50
	v_lshlrev_b64 v[198:199], 16, v[50:51]
	v_add_u32_e32 v1, 0x60000, v1
	v_add_u32_e32 v0, v0, v198
	v_subrev_u32_e32 v0, s74, v0
	v_mov_b32_e32 v130, v1
	v_mov_b32_e32 v134, v0
	s_lshl_b32 s5, s3, 13
	s_add_u32 s20, s14, s5
	s_movk_i32 s5, 0x100
	v_cmp_gt_i32_e64 s[42:43], s5, v40
	s_movk_i32 s5, 0xff
	v_readfirstlane_b32 s4, v40
	s_addc_u32 s21, s15, 0
	v_cmp_lt_i32_e32 vcc, s5, v40
	s_and_saveexec_b64 s[14:15], vcc
	s_xor_b64 s[44:45], exec, s[14:15]
	v_mov_b32_e32 v41, v97
	s_or_saveexec_b64 s[44:45], s[44:45]
	s_lshl_b32 s11, s2, 8
	s_lshl_b32 s5, s3, 6
	v_mov_b32_e32 v175, 0
	v_mov_b32_e32 v189, 0
	s_xor_b64 exec, exec, s[44:45]
	s_cbranch_execz .LBB0_146
	s_lshl_b32 s3, s11, 2
	s_add_u32 s14, s20, s3
	s_addc_u32 s15, s21, 0
	v_ashrrev_i32_e32 v41, 31, v40
	v_lshl_add_u64 v[0:1], v[40:41], 2, s[14:15]
	global_load_dword v189, v[0:1], off sc1
.LBB0_146:
	s_or_b64 exec, exec, s[44:45]
	s_ashr_i32 s3, s4, 1
	s_andn2_b32 s3, s3, 31
	v_and_b32_e32 v47, 31, v40
	s_add_i32 s3, s3, s11
	v_or_b32_e32 v202, s3, v47
	v_ashrrev_i32_e32 v203, 31, v202
	v_lshl_add_u64 v[0:1], v[202:203], 2, s[20:21]
	global_load_dword v237, v[0:1], off sc1
	v_lshl_add_u64 v[0:1], s[36:37], 0, v[202:203]
	v_readlane_b32 s14, v253, 43
	v_lshlrev_b64 v[0:1], 11, v[0:1]
	v_readlane_b32 s15, v253, 44
	v_bfe_u32 v45, v40, 5, 1
	s_lshl_b32 s36, s5, 1
	v_lshl_add_u64 v[0:1], s[14:15], 0, v[0:1]
	v_lshl_add_u64 v[200:201], v[0:1], 0, s[36:37]
	v_lshlrev_b32_e32 v49, 4, v45
	v_add_u32_e32 v0, v200, v49
	v_subrev_u32_e32 v4, s74, v0
	buffer_load_dwordx4 v[0:3], v4, s[76:79], 0 offen sc1
	buffer_load_dwordx4 v[36:39], v4, s[76:79], 0 offen offset:32 sc1
	buffer_load_dwordx4 v[74:77], v4, s[76:79], 0 offen offset:64 sc1
	buffer_load_dwordx4 v[62:65], v4, s[76:79], 0 offen offset:96 sc1
	v_and_b32_e32 v5, 64, v227
	v_xor_b32_e32 v4, 32, v227
	v_add_u32_e32 v51, 64, v5
	s_lshl_b32 s5, s5, 2
	v_cmp_lt_i32_e32 vcc, v4, v51
	s_add_u32 s14, s70, s5
	s_addc_u32 s15, s71, 0
	v_cndmask_b32_e32 v4, v227, v4, vcc
	v_lshlrev_b32_e32 v8, 5, v45
	v_lshlrev_b32_e32 v140, 2, v4
	global_load_dwordx4 v[28:31], v8, s[14:15] offset:16
	global_load_dwordx4 v[32:35], v8, s[14:15]
	global_load_dwordx4 v[20:23], v8, s[14:15] offset:80
	global_load_dwordx4 v[24:27], v8, s[14:15] offset:64
	global_load_dwordx4 v[12:15], v8, s[14:15] offset:144
	global_load_dwordx4 v[16:19], v8, s[14:15] offset:128
	global_load_dwordx4 v[4:7], v8, s[14:15] offset:208
	s_nop 0
	global_load_dwordx4 v[8:11], v8, s[14:15] offset:192
	buffer_load_dwordx4 v[106:109], v106, s[76:79], 0 offen sc1
	buffer_load_dwordx4 v[110:113], v110, s[76:79], 0 offen sc1
	buffer_load_dwordx4 v[114:117], v114, s[76:79], 0 offen sc1
	buffer_load_dwordx4 v[118:121], v118, s[76:79], 0 offen sc1
	buffer_load_dwordx4 v[122:125], v122, s[76:79], 0 offen sc1
	buffer_load_dwordx4 v[126:129], v126, s[76:79], 0 offen sc1
	buffer_load_dwordx4 v[130:133], v130, s[76:79], 0 offen sc1
	buffer_load_dwordx4 v[134:137], v134, s[76:79], 0 offen sc1
	s_movk_i32 s11, 0x210
	v_mul_lo_u32 v218, v44, s11
	v_mul_lo_u32 v219, v46, s11
	v_mul_lo_u32 v220, v48, s11
	v_mul_lo_u32 v221, v50, s11
	v_readlane_b32 s11, v254, 25
	v_lshl_add_u64 v[206:207], v[40:41], 2, s[20:21]
	v_lshlrev_b32_e32 v193, 2, v45
	v_add_u32_e32 v231, 0, v49
	v_mov_b32_e32 v41, v97
	v_mov_b32_e32 v44, v97
	v_mov_b32_e32 v46, v97
	s_mov_b32 s4, 0
	s_or_b32 s5, s3, 31
	v_mov_b32_e32 v234, 0
	s_waitcnt vmcnt(19)
	v_lshlrev_b32_e32 v86, 16, v3
	v_and_b32_e32 v87, 0xffff0000, v3
	v_lshlrev_b32_e32 v92, 16, v1
	s_waitcnt vmcnt(16)
	v_and_b32_e32 v53, 0xffff0000, v65
	v_and_b32_e32 v55, 0xffff0000, v64
	v_lshlrev_b32_e32 v52, 16, v65
	v_lshlrev_b32_e32 v54, 16, v64
	v_mov_b32_e32 v58, v53
	v_mov_b32_e32 v59, v55
	v_mov_b32_e32 v56, v52
	v_mov_b32_e32 v57, v54
	v_pk_mul_f32 v[58:59], v[58:59], v[58:59]
	v_and_b32_e32 v93, 0xffff0000, v1
	v_pk_fma_f32 v[60:61], v[56:57], v[56:57], v[58:59]
	v_and_b32_e32 v57, 0xffff0000, v63
	v_and_b32_e32 v59, 0xffff0000, v62
	v_lshlrev_b32_e32 v56, 16, v63
	v_lshlrev_b32_e32 v58, 16, v62
	v_mov_b32_e32 v64, v57
	v_mov_b32_e32 v65, v59
	v_mov_b32_e32 v62, v56
	v_mov_b32_e32 v63, v58
	v_pk_mul_f32 v[64:65], v[64:65], v[64:65]
	v_lshlrev_b32_e32 v138, 16, v0
	v_pk_fma_f32 v[66:67], v[62:63], v[62:63], v[64:65]
	v_and_b32_e32 v63, 0xffff0000, v77
	v_and_b32_e32 v65, 0xffff0000, v76
	v_lshlrev_b32_e32 v62, 16, v77
	v_lshlrev_b32_e32 v64, 16, v76
	v_mov_b32_e32 v70, v63
	v_mov_b32_e32 v71, v65
	v_mov_b32_e32 v68, v62
	v_mov_b32_e32 v69, v64
	v_pk_mul_f32 v[70:71], v[70:71], v[70:71]
	v_and_b32_e32 v139, 0xffff0000, v0
	v_pk_fma_f32 v[72:73], v[68:69], v[68:69], v[70:71]
	v_and_b32_e32 v69, 0xffff0000, v75
	v_and_b32_e32 v71, 0xffff0000, v74
	v_lshlrev_b32_e32 v68, 16, v75
	v_lshlrev_b32_e32 v70, 16, v74
	v_mov_b32_e32 v76, v69
	v_mov_b32_e32 v77, v71
	v_mov_b32_e32 v74, v68
	v_mov_b32_e32 v75, v70
	v_pk_mul_f32 v[76:77], v[76:77], v[76:77]
	v_and_b32_e32 v79, 0xffff0000, v38
	v_pk_fma_f32 v[76:77], v[74:75], v[74:75], v[76:77]
	v_and_b32_e32 v75, 0xffff0000, v39
	v_pk_mul_f32 v[88:89], v[86:87], v[86:87]
	v_lshlrev_b32_e32 v90, 16, v2
	v_and_b32_e32 v91, 0xffff0000, v2
	v_pk_mul_f32 v[94:95], v[92:93], v[92:93]
	v_pk_mul_f32 v[0:1], v[138:139], v[138:139]
	v_lshlrev_b32_e32 v74, 16, v39
	v_lshlrev_b32_e32 v78, 16, v38
	v_mov_b32_e32 v80, v75
	v_mov_b32_e32 v81, v79
	v_pk_mul_f32 v[2:3], v[90:91], v[90:91]
	v_add_f32_e32 v88, v88, v89
	v_add_f32_e32 v89, v94, v95
	v_add_f32_e32 v0, v0, v1
	v_mov_b32_e32 v38, v74
	v_mov_b32_e32 v39, v78
	v_pk_mul_f32 v[80:81], v[80:81], v[80:81]
	v_lshlrev_b32_e32 v84, 16, v36
	v_and_b32_e32 v85, 0xffff0000, v36
	v_add_f32_e32 v0, v0, v89
	v_add_f32_e32 v1, v2, v3
	v_pk_fma_f32 v[38:39], v[38:39], v[38:39], v[80:81]
	v_lshlrev_b32_e32 v80, 16, v37
	v_and_b32_e32 v81, 0xffff0000, v37
	v_pk_mul_f32 v[36:37], v[84:85], v[84:85]
	v_add_f32_e32 v0, v1, v0
	v_pk_mul_f32 v[82:83], v[80:81], v[80:81]
	v_add_f32_e32 v0, v88, v0
	v_add_f32_e32 v1, v36, v37
	v_add_f32_e32 v0, v1, v0
	v_add_f32_e32 v1, v82, v83
	v_add_f32_e32 v0, v1, v0
	v_add_f32_e32 v0, v39, v0
	v_add_f32_e32 v0, v38, v0
	v_add_f32_e32 v0, v77, v0
	v_add_f32_e32 v0, v76, v0
	v_add_f32_e32 v0, v73, v0
	v_add_f32_e32 v0, v72, v0
	v_add_f32_e32 v0, v67, v0
	v_add_f32_e32 v0, v66, v0
	v_add_f32_e32 v0, v61, v0
	v_add_f32_e32 v0, v60, v0
	ds_bpermute_b32 v1, v140, v0
	v_mov_b32_e32 v36, v97
	v_mov_b32_e32 v37, v97
	v_mov_b32_e32 v38, v97
	v_mov_b32_e32 v39, v97
	s_waitcnt lgkmcnt(0)
	v_add_f32_e32 v0, v0, v1
	v_fmamk_f32 v0, v0, 0x3c800000, v225
	v_cmp_gt_f32_e32 vcc, s30, v0
	v_mul_f32_e32 v1, 0x4b800000, v0
	s_nop 0
	v_cndmask_b32_e32 v0, v0, v1, vcc
	v_rsq_f32_e32 v0, v0
	s_nop 0
	v_mul_f32_e32 v1, 0x45800000, v0
	v_cndmask_b32_e32 v0, v0, v1, vcc
	v_mul_f32_e32 v0, 0x3e38aa3b, v0
	v_pk_mul_f32 v[2:3], v[0:1], v[138:139] op_sel_hi:[0,1]
	s_waitcnt vmcnt(14)
	v_pk_mul_f32 v[2:3], v[32:33], v[2:3]
	v_mov_b32_e32 v32, v97
	v_cvt_pk_bf16_f32 v138, v2, v3
	v_pk_mul_f32 v[2:3], v[0:1], v[92:93] op_sel_hi:[0,1]
	v_pk_mul_f32 v[2:3], v[34:35], v[2:3]
	v_mov_b32_e32 v33, v97
	v_cvt_pk_bf16_f32 v139, v2, v3
	v_pk_mul_f32 v[2:3], v[0:1], v[90:91] op_sel_hi:[0,1]
	v_pk_mul_f32 v[2:3], v[28:29], v[2:3]
	v_mov_b32_e32 v34, v97
	v_cvt_pk_bf16_f32 v140, v2, v3
	v_pk_mul_f32 v[2:3], v[0:1], v[86:87] op_sel_hi:[0,1]
	v_pk_mul_f32 v[2:3], v[30:31], v[2:3]
	v_mov_b32_e32 v35, v97
	v_cvt_pk_bf16_f32 v141, v2, v3
	v_pk_mul_f32 v[2:3], v[0:1], v[84:85] op_sel_hi:[0,1]
	s_waitcnt vmcnt(12)
	v_pk_mul_f32 v[2:3], v[24:25], v[2:3]
	s_nop 0
	v_cvt_pk_bf16_f32 v142, v2, v3
	v_pk_mul_f32 v[2:3], v[0:1], v[80:81] op_sel_hi:[0,1]
	v_pk_mul_f32 v[2:3], v[26:27], v[2:3]
	s_nop 0
	v_cvt_pk_bf16_f32 v143, v2, v3
	v_pk_mul_f32 v[2:3], v[0:1], v[78:79] op_sel_hi:[0,1]
	v_pk_mul_f32 v[2:3], v[20:21], v[2:3]
	s_nop 0
	v_cvt_pk_bf16_f32 v144, v2, v3
	v_pk_mul_f32 v[2:3], v[0:1], v[74:75] op_sel_hi:[0,1]
	v_pk_mul_f32 v[2:3], v[22:23], v[2:3]
	s_nop 0
	v_cvt_pk_bf16_f32 v145, v2, v3
	v_pk_mul_f32 v[2:3], v[0:1], v[70:71] op_sel_hi:[0,1]
	s_waitcnt vmcnt(10)
	v_pk_mul_f32 v[2:3], v[16:17], v[2:3]
	v_xor_b32_e32 v16, 1, v227
	v_cvt_pk_bf16_f32 v146, v2, v3
	v_pk_mul_f32 v[2:3], v[0:1], v[68:69] op_sel_hi:[0,1]
	v_pk_mul_f32 v[2:3], v[18:19], v[2:3]
	v_cmp_lt_i32_e32 vcc, v16, v51
	v_cvt_pk_bf16_f32 v147, v2, v3
	v_pk_mul_f32 v[2:3], v[0:1], v[64:65] op_sel_hi:[0,1]
	v_pk_mul_f32 v[2:3], v[12:13], v[2:3]
	v_cndmask_b32_e32 v16, v227, v16, vcc
	v_cvt_pk_bf16_f32 v148, v2, v3
	v_pk_mul_f32 v[2:3], v[0:1], v[62:63] op_sel_hi:[0,1]
	v_pk_mul_f32 v[2:3], v[14:15], v[2:3]
	v_lshlrev_b32_e32 v191, 2, v16
	v_cvt_pk_bf16_f32 v149, v2, v3
	v_pk_mul_f32 v[2:3], v[0:1], v[58:59] op_sel_hi:[0,1]
	s_waitcnt vmcnt(8)
	v_pk_mul_f32 v[2:3], v[8:9], v[2:3]
	v_xor_b32_e32 v16, 2, v227
	v_cvt_pk_bf16_f32 v150, v2, v3
	v_pk_mul_f32 v[2:3], v[0:1], v[56:57] op_sel_hi:[0,1]
	v_pk_mul_f32 v[2:3], v[10:11], v[2:3]
	v_cmp_lt_i32_e32 vcc, v16, v51
	v_cvt_pk_bf16_f32 v151, v2, v3
	v_pk_mul_f32 v[2:3], v[0:1], v[54:55] op_sel_hi:[0,1]
	v_pk_mul_f32 v[0:1], v[0:1], v[52:53] op_sel_hi:[0,1]
	v_pk_mul_f32 v[0:1], v[6:7], v[0:1]
	v_cndmask_b32_e32 v16, v227, v16, vcc
	v_cvt_pk_bf16_f32 v153, v0, v1
	s_nop 0
	v_mov_b32_e32 v0, v237
	v_lshlrev_b32_e32 v195, 2, v16
	v_xor_b32_e32 v16, 4, v227
	v_cmp_lt_i32_e32 vcc, v16, v51
	v_mov_b32_e32 v17, v97
	v_pk_mul_f32 v[2:3], v[4:5], v[2:3]
	v_cndmask_b32_e32 v16, v227, v16, vcc
	v_lshlrev_b32_e32 v197, 2, v16
	v_lshlrev_b32_e32 v16, 4, v40
	v_and_b32_e32 v199, 0x1f0, v16
	v_lshlrev_b32_e32 v16, 1, v43
	v_lshl_add_u64 v[204:205], s[12:13], 0, v[16:17]
	v_mul_u32_u24_e32 v17, 0x210, v47
	v_lshl_or_b32 v17, v45, 3, v17
	v_mul_u32_u24_e32 v16, 0x90, v47
	v_add_u32_e32 v232, s11, v17
	v_readlane_b32 s11, v254, 26
	v_cvt_pk_bf16_f32 v152, v2, v3
	v_lshlrev_b32_e32 v203, 2, v40
	v_mul_lo_u32 v205, v42, s93
	v_add3_u32 v233, v16, v49, s11
	v_mov_b32_e32 v40, v97
	v_mov_b32_e32 v42, v97
	v_mov_b32_e32 v43, v97
	v_mov_b32_e32 v45, v97
	v_mov_b32_e32 v47, v97
	v_mov_b64_e32 v[16:17], v[32:33]
	s_mov_b64 s[20:21], -1
	v_mov_b64_e32 v[18:19], v[34:35]
	v_mov_b64_e32 v[20:21], v[36:37]
	v_mov_b64_e32 v[22:23], v[38:39]
	v_mov_b64_e32 v[24:25], v[40:41]
	v_mov_b64_e32 v[26:27], v[42:43]
	v_mov_b64_e32 v[28:29], v[44:45]
	v_mov_b64_e32 v[30:31], v[46:47]
	s_waitcnt vmcnt(0)
	v_mov_b32_e32 v14, v0
	v_mov_b32_e32 v15, v0
	v_mov_b32_e32 v1, v0
	v_mov_b32_e32 v2, v0
	v_mov_b32_e32 v3, v0
	v_mov_b32_e32 v4, v0
	v_mov_b32_e32 v5, v0
	v_mov_b32_e32 v6, v0
	v_mov_b32_e32 v7, v0
	v_mov_b32_e32 v8, v0
	v_mov_b32_e32 v9, v0
	v_mov_b32_e32 v10, v0
	v_mov_b32_e32 v11, v0
	v_mov_b32_e32 v12, v0
	v_mov_b32_e32 v13, v0
	v_mov_b64_e32 v[62:63], v[14:15]
	v_mov_b64_e32 v[60:61], v[12:13]
	v_mov_b64_e32 v[58:59], v[10:11]
	v_mov_b64_e32 v[56:57], v[8:9]
	v_mov_b64_e32 v[54:55], v[6:7]
	v_mov_b64_e32 v[52:53], v[4:5]
	v_mov_b64_e32 v[50:51], v[2:3]
	v_mov_b64_e32 v[48:49], v[0:1]
	s_branch .LBB0_148
